# speedup vs baseline: 1.0128x; 1.0042x over previous
;     __device__ __forceinline__ float rowscale(int r) const { return rsmode == 1 ? rs[r] : (rsmode == 2 ? rsqrtf((float)rs64[r] * (RSS_UNFIX * rsinv) + EPS) : 1.f); }
;     __device__ __forceinline__ void operator()(const pg8::f32x4 (&acc)[2][2][4][2], const pg8::Unit& u, int wr, int wc, int fr, int fq) const {
;     ...
;         if (mode >= 5) {
;             const bool hasF = mode == 5, outF = mode == 7;
;             u32x4 cb2 = {0u, 0u, 0u, 0u}, nb2 = cb2, cbb, nbb; float csc, nsc = 1.f, ss = 0.f;
;             {
;                 if (hasF) cb2 = *(const u32x4*)(base2 + (size_t)row0 * 1024 + col0);
;                 cbb = *(const u32x4*)(baseb + (size_t)row0 * 1024 + col0);
;                 csc = rowscale(row0);
;             }
;             nbb = cbb;
; #pragma unroll
;             for (int p = 0; p < 16; ++p) {
;                 const int g = p >> 1, bj = p & 1, ai = g >> 2, m = g & 3, r = row0 + ai * 128 + m * 16, c = col0 + bj * 128;
;                 if (p < 15) {
;                     const int gn = (p + 1) >> 1, rn = row0 + (gn >> 2) * 128 + (gn & 3) * 16, cn = col0 + ((p + 1) & 1) * 128;
;                     if (hasF) nb2 = *(const u32x4*)(base2 + (size_t)rn * 1024 + cn);
;                     nbb = *(const u32x4*)(baseb + (size_t)rn * 1024 + cn);
;                     if (bj == 1) nsc = rowscale(rn);
;                 }
;                 const f32x4 r0 = {bflo(cbb.x), bfhi(cbb.x), bflo(cbb.y), bfhi(cbb.y)}, r1 = {bflo(cbb.z), bfhi(cbb.z), bflo(cbb.w), bfhi(cbb.w)};
;                 const f32x4 q0 = {bflo(cb2.x), bfhi(cb2.x), bflo(cb2.y), bfhi(cb2.y)}, q1 = {bflo(cb2.z), bfhi(cb2.z), bflo(cb2.w), bfhi(cb2.w)};
;                 const f32x4 v0 = acc[ai][bj][m][0] * csc + q0 + r0, v1 = acc[ai][bj][m][1] * csc + q1 + r1;
;                 if (outF) {
;                     float* op = out + (size_t)r * 1024 + c;
;                     *(f32x4*)op = v0; *(f32x4*)(op + 4) = v1;
;                 } else {
.LBB0_1038:
	v_lshl_add_u32 v144, s16, 8, v148
	v_lshl_or_b32 v162, s39, 8, v150
	v_ashrrev_i32_e32 v145, 31, v144
	v_lshlrev_b64 v[146:147], 11, v[144:145]
	v_ashrrev_i32_e32 v163, 31, v162
	v_lshl_add_u64 v[154:155], s[78:79], 0, v[146:147]
	v_lshlrev_b64 v[146:147], 1, v[162:163]
	v_lshl_add_u64 v[158:159], v[154:155], 0, v[146:147]
	global_load_dwordx4 v[154:157], v[158:159], off
	s_nop 0
	global_load_dwordx4 v[158:161], v[158:159], off offset:256
	v_or_b32_e32 v174, 16, v144
	v_pk_add_f32 v[170:171], v[114:115], 0 op_sel_hi:[1,0]
	v_lshlrev_b64 v[114:115], 12, v[144:145]
	v_ashrrev_i32_e32 v175, 31, v174
	v_pk_add_f32 v[168:169], v[116:117], 0 op_sel_hi:[1,0]
	v_pk_add_f32 v[172:173], v[112:113], 0 op_sel_hi:[1,0]
	v_lshlrev_b64 v[112:113], 2, v[162:163]
	v_lshl_add_u64 v[114:115], s[76:77], 0, v[114:115]
	v_lshlrev_b64 v[116:117], 11, v[174:175]
	v_lshl_add_u64 v[162:163], v[114:115], 0, v[112:113]
	v_lshl_add_u64 v[114:115], s[78:79], 0, v[116:117]
	v_pk_add_f32 v[126:127], v[126:127], 0 op_sel_hi:[1,0]
	v_pk_add_f32 v[124:125], v[124:125], 0 op_sel_hi:[1,0]
	v_pk_add_f32 v[122:123], v[122:123], 0 op_sel_hi:[1,0]
	v_pk_add_f32 v[164:165], v[120:121], 0 op_sel_hi:[1,0]
	v_pk_add_f32 v[166:167], v[118:119], 0 op_sel_hi:[1,0]
	v_lshl_add_u64 v[176:177], v[114:115], 0, v[146:147]
	v_pk_add_f32 v[110:111], v[110:111], 0 op_sel_hi:[1,0]
	v_pk_add_f32 v[108:109], v[108:109], 0 op_sel_hi:[1,0]
	v_pk_add_f32 v[106:107], v[106:107], 0 op_sel_hi:[1,0]
	v_pk_add_f32 v[104:105], v[104:105], 0 op_sel_hi:[1,0]
	v_pk_add_f32 v[94:95], v[94:95], 0 op_sel_hi:[1,0]
	v_pk_add_f32 v[92:93], v[92:93], 0 op_sel_hi:[1,0]
	v_pk_add_f32 v[90:91], v[90:91], 0 op_sel_hi:[1,0]
	v_pk_add_f32 v[88:89], v[88:89], 0 op_sel_hi:[1,0]
	v_pk_add_f32 v[78:79], v[78:79], 0 op_sel_hi:[1,0]
	v_pk_add_f32 v[76:77], v[76:77], 0 op_sel_hi:[1,0]
	v_pk_add_f32 v[74:75], v[74:75], 0 op_sel_hi:[1,0]
	v_pk_add_f32 v[72:73], v[72:73], 0 op_sel_hi:[1,0]
	v_pk_add_f32 v[62:63], v[62:63], 0 op_sel_hi:[1,0]
	v_pk_add_f32 v[60:61], v[60:61], 0 op_sel_hi:[1,0]
	v_pk_add_f32 v[58:59], v[58:59], 0 op_sel_hi:[1,0]
	v_pk_add_f32 v[56:57], v[56:57], 0 op_sel_hi:[1,0]
	v_pk_add_f32 v[46:47], v[46:47], 0 op_sel_hi:[1,0]
	v_pk_add_f32 v[44:45], v[44:45], 0 op_sel_hi:[1,0]
	v_pk_add_f32 v[42:43], v[42:43], 0 op_sel_hi:[1,0]
	v_pk_add_f32 v[40:41], v[40:41], 0 op_sel_hi:[1,0]
	v_pk_add_f32 v[30:31], v[30:31], 0 op_sel_hi:[1,0]
	v_pk_add_f32 v[28:29], v[28:29], 0 op_sel_hi:[1,0]
	v_pk_add_f32 v[26:27], v[26:27], 0 op_sel_hi:[1,0]
	v_pk_add_f32 v[24:25], v[24:25], 0 op_sel_hi:[1,0]
	v_pk_add_f32 v[14:15], v[14:15], 0 op_sel_hi:[1,0]
	v_pk_add_f32 v[12:13], v[12:13], 0 op_sel_hi:[1,0]
	v_pk_add_f32 v[10:11], v[10:11], 0 op_sel_hi:[1,0]
	v_pk_add_f32 v[8:9], v[8:9], 0 op_sel_hi:[1,0]
	s_andn2_b64 vcc, exec, s[0:1]
	s_mov_b64 s[0:1], -1
	s_waitcnt vmcnt(0)
	v_lshlrev_b32_e32 v114, 16, v154
	v_and_b32_e32 v115, 0xffff0000, v154
	v_lshlrev_b32_e32 v116, 16, v155
	v_and_b32_e32 v117, 0xffff0000, v155
	v_lshlrev_b32_e32 v118, 16, v156
	v_and_b32_e32 v119, 0xffff0000, v156
	v_lshlrev_b32_e32 v120, 16, v157
	v_and_b32_e32 v121, 0xffff0000, v157
	v_lshlrev_b32_e32 v154, 16, v158
	v_and_b32_e32 v155, 0xffff0000, v158
	v_lshlrev_b32_e32 v156, 16, v159
	v_pk_add_f32 v[116:117], v[126:127], v[116:117]
	v_pk_add_f32 v[114:115], v[124:125], v[114:115]
	v_pk_add_f32 v[120:121], v[122:123], v[120:121]
	v_pk_add_f32 v[118:119], v[164:165], v[118:119]
	v_and_b32_e32 v157, 0xffff0000, v159
	global_store_dwordx4 v[162:163], v[114:117], off nt
	global_store_dwordx4 v[162:163], v[118:121], off offset:16 nt
	v_lshlrev_b32_e32 v122, 16, v160
	v_and_b32_e32 v123, 0xffff0000, v160
	v_lshlrev_b32_e32 v124, 16, v161
	v_and_b32_e32 v125, 0xffff0000, v161
	v_pk_add_f32 v[120:121], v[166:167], v[156:157]
	v_pk_add_f32 v[118:119], v[168:169], v[154:155]
	global_load_dwordx4 v[114:117], v[176:177], off
	v_pk_add_f32 v[124:125], v[170:171], v[124:125]
	v_pk_add_f32 v[122:123], v[172:173], v[122:123]
	global_store_dwordx4 v[162:163], v[118:121], off offset:512 nt
	global_store_dwordx4 v[162:163], v[122:125], off offset:528 nt
	global_load_dwordx4 v[118:121], v[176:177], off offset:256
	v_or_b32_e32 v156, 32, v144
	v_ashrrev_i32_e32 v157, 31, v156
	v_pk_add_f32 v[126:127], v[98:99], 0 op_sel_hi:[1,0]
	v_pk_add_f32 v[154:155], v[96:97], 0 op_sel_hi:[1,0]
	v_lshlrev_b64 v[96:97], 12, v[174:175]
	v_lshlrev_b64 v[98:99], 11, v[156:157]
	v_lshl_add_u64 v[96:97], s[76:77], 0, v[96:97]
	v_lshl_add_u64 v[98:99], s[78:79], 0, v[98:99]
	v_pk_add_f32 v[122:123], v[102:103], 0 op_sel_hi:[1,0]
	v_pk_add_f32 v[124:125], v[100:101], 0 op_sel_hi:[1,0]
	v_lshl_add_u64 v[158:159], v[96:97], 0, v[112:113]
	v_lshl_add_u64 v[160:161], v[98:99], 0, v[146:147]
	s_waitcnt vmcnt(3)
	v_lshlrev_b32_e32 v96, 16, v114
	v_and_b32_e32 v97, 0xffff0000, v114
	v_lshlrev_b32_e32 v98, 16, v115
	v_and_b32_e32 v99, 0xffff0000, v115
	v_lshlrev_b32_e32 v100, 16, v116
	v_and_b32_e32 v101, 0xffff0000, v116
	v_lshlrev_b32_e32 v102, 16, v117
	v_and_b32_e32 v103, 0xffff0000, v117
	v_pk_add_f32 v[98:99], v[110:111], v[98:99]
	v_pk_add_f32 v[96:97], v[108:109], v[96:97]
	v_pk_add_f32 v[102:103], v[106:107], v[102:103]
	v_pk_add_f32 v[100:101], v[104:105], v[100:101]
	s_waitcnt vmcnt(0)
;     __device__ __forceinline__ float rowscale(int r) const { return rsmode == 1 ? rs[r] : (rsmode == 2 ? rsqrtf((float)rs64[r] * (RSS_UNFIX * rsinv) + EPS) : 1.f); }
;     __device__ __forceinline__ void operator()(const pg8::f32x4 (&acc)[2][2][4][2], const pg8::Unit& u, int wr, int wc, int fr, int fq) const {
;     ...
;         if (mode >= 5) {
;             const bool hasF = mode == 5, outF = mode == 7;
;             u32x4 cb2 = {0u, 0u, 0u, 0u}, nb2 = cb2, cbb, nbb; float csc, nsc = 1.f, ss = 0.f;
;             {
;                 if (hasF) cb2 = *(const u32x4*)(base2 + (size_t)row0 * 1024 + col0);
;                 cbb = *(const u32x4*)(baseb + (size_t)row0 * 1024 + col0);
;                 csc = rowscale(row0);
;             }
;             nbb = cbb;
; #pragma unroll
;             for (int p = 0; p < 16; ++p) {
;                 const int g = p >> 1, bj = p & 1, ai = g >> 2, m = g & 3, r = row0 + ai * 128 + m * 16, c = col0 + bj * 128;
;                 if (p < 15) {
;                     const int gn = (p + 1) >> 1, rn = row0 + (gn >> 2) * 128 + (gn & 3) * 16, cn = col0 + ((p + 1) & 1) * 128;
;                     if (hasF) nb2 = *(const u32x4*)(base2 + (size_t)rn * 1024 + cn);
;                     nbb = *(const u32x4*)(baseb + (size_t)rn * 1024 + cn);
;                     if (bj == 1) nsc = rowscale(rn);
;                 }
;                 const f32x4 r0 = {bflo(cbb.x), bfhi(cbb.x), bflo(cbb.y), bfhi(cbb.y)}, r1 = {bflo(cbb.z), bfhi(cbb.z), bflo(cbb.w), bfhi(cbb.w)};
;                 const f32x4 q0 = {bflo(cb2.x), bfhi(cb2.x), bflo(cb2.y), bfhi(cb2.y)}, q1 = {bflo(cb2.z), bfhi(cb2.z), bflo(cb2.w), bfhi(cb2.w)};
;                 const f32x4 v0 = acc[ai][bj][m][0] * csc + q0 + r0, v1 = acc[ai][bj][m][1] * csc + q1 + r1;
;                 if (outF) {
;                     float* op = out + (size_t)r * 1024 + c;
;                     *(f32x4*)op = v0; *(f32x4*)(op + 4) = v1;
;                 } else {
	v_lshlrev_b32_e32 v104, 16, v118
	v_and_b32_e32 v105, 0xffff0000, v118
	v_lshlrev_b32_e32 v106, 16, v119
	v_and_b32_e32 v107, 0xffff0000, v119
	global_store_dwordx4 v[158:159], v[96:99], off nt
	global_store_dwordx4 v[158:159], v[100:103], off offset:16 nt
	v_lshlrev_b32_e32 v108, 16, v120
	v_and_b32_e32 v109, 0xffff0000, v120
	v_lshlrev_b32_e32 v110, 16, v121
	v_and_b32_e32 v111, 0xffff0000, v121
	v_pk_add_f32 v[102:103], v[122:123], v[106:107]
	v_pk_add_f32 v[100:101], v[124:125], v[104:105]
	global_load_dwordx4 v[96:99], v[160:161], off
	v_pk_add_f32 v[106:107], v[126:127], v[110:111]
	v_pk_add_f32 v[104:105], v[154:155], v[108:109]
	global_store_dwordx4 v[158:159], v[100:103], off offset:512 nt
	global_store_dwordx4 v[158:159], v[104:107], off offset:528 nt
	global_load_dwordx4 v[100:103], v[160:161], off offset:256
	v_or_b32_e32 v114, 48, v144
	v_ashrrev_i32_e32 v115, 31, v114
	v_pk_add_f32 v[108:109], v[82:83], 0 op_sel_hi:[1,0]
	v_pk_add_f32 v[110:111], v[80:81], 0 op_sel_hi:[1,0]
	v_lshlrev_b64 v[80:81], 12, v[156:157]
	v_lshlrev_b64 v[82:83], 11, v[114:115]
	v_lshl_add_u64 v[80:81], s[76:77], 0, v[80:81]
	v_lshl_add_u64 v[82:83], s[78:79], 0, v[82:83]
	v_pk_add_f32 v[104:105], v[86:87], 0 op_sel_hi:[1,0]
	v_pk_add_f32 v[106:107], v[84:85], 0 op_sel_hi:[1,0]
	v_lshl_add_u64 v[116:117], v[80:81], 0, v[112:113]
	v_lshl_add_u64 v[118:119], v[82:83], 0, v[146:147]
	s_waitcnt vmcnt(3)
	v_lshlrev_b32_e32 v80, 16, v96
	v_and_b32_e32 v81, 0xffff0000, v96
	v_lshlrev_b32_e32 v82, 16, v97
	v_and_b32_e32 v83, 0xffff0000, v97
	v_lshlrev_b32_e32 v84, 16, v98
	v_and_b32_e32 v85, 0xffff0000, v98
	v_lshlrev_b32_e32 v86, 16, v99
	v_and_b32_e32 v87, 0xffff0000, v99
	v_pk_add_f32 v[82:83], v[94:95], v[82:83]
	v_pk_add_f32 v[80:81], v[92:93], v[80:81]
	v_pk_add_f32 v[86:87], v[90:91], v[86:87]
	v_pk_add_f32 v[84:85], v[88:89], v[84:85]
	s_waitcnt vmcnt(0)
	v_lshlrev_b32_e32 v88, 16, v100
	v_and_b32_e32 v89, 0xffff0000, v100
	v_lshlrev_b32_e32 v90, 16, v101
	v_and_b32_e32 v91, 0xffff0000, v101
	global_store_dwordx4 v[116:117], v[80:83], off nt
	global_store_dwordx4 v[116:117], v[84:87], off offset:16 nt
	v_lshlrev_b32_e32 v92, 16, v102
	v_and_b32_e32 v93, 0xffff0000, v102
	v_lshlrev_b32_e32 v94, 16, v103
	v_and_b32_e32 v95, 0xffff0000, v103
	v_pk_add_f32 v[86:87], v[104:105], v[90:91]
	v_pk_add_f32 v[84:85], v[106:107], v[88:89]
	global_load_dwordx4 v[80:83], v[118:119], off
	v_pk_add_f32 v[90:91], v[108:109], v[94:95]
	v_pk_add_f32 v[88:89], v[110:111], v[92:93]
	global_store_dwordx4 v[116:117], v[84:87], off offset:512 nt
	global_store_dwordx4 v[116:117], v[88:91], off offset:528 nt
	global_load_dwordx4 v[84:87], v[118:119], off offset:256
	v_add_u32_e32 v96, 0x80, v144
	v_ashrrev_i32_e32 v97, 31, v96
	v_pk_add_f32 v[92:93], v[66:67], 0 op_sel_hi:[1,0]
	v_pk_add_f32 v[94:95], v[64:65], 0 op_sel_hi:[1,0]
	v_lshlrev_b64 v[64:65], 12, v[114:115]
	v_lshlrev_b64 v[66:67], 11, v[96:97]
	v_lshl_add_u64 v[64:65], s[76:77], 0, v[64:65]
	v_lshl_add_u64 v[66:67], s[78:79], 0, v[66:67]
	v_pk_add_f32 v[88:89], v[70:71], 0 op_sel_hi:[1,0]
	v_pk_add_f32 v[90:91], v[68:69], 0 op_sel_hi:[1,0]
	v_lshl_add_u64 v[98:99], v[64:65], 0, v[112:113]
	v_lshl_add_u64 v[100:101], v[66:67], 0, v[146:147]
	s_waitcnt vmcnt(3)
	v_lshlrev_b32_e32 v64, 16, v80
	v_and_b32_e32 v65, 0xffff0000, v80
	v_lshlrev_b32_e32 v66, 16, v81
	v_and_b32_e32 v67, 0xffff0000, v81
	v_lshlrev_b32_e32 v68, 16, v82
	v_and_b32_e32 v69, 0xffff0000, v82
	v_lshlrev_b32_e32 v70, 16, v83
	v_and_b32_e32 v71, 0xffff0000, v83
	v_pk_add_f32 v[66:67], v[78:79], v[66:67]
	v_pk_add_f32 v[64:65], v[76:77], v[64:65]
	v_pk_add_f32 v[70:71], v[74:75], v[70:71]
	v_pk_add_f32 v[68:69], v[72:73], v[68:69]
	s_waitcnt vmcnt(0)
	v_lshlrev_b32_e32 v72, 16, v84
	v_and_b32_e32 v73, 0xffff0000, v84
	v_lshlrev_b32_e32 v74, 16, v85
	v_and_b32_e32 v75, 0xffff0000, v85
	global_store_dwordx4 v[98:99], v[64:67], off nt
	global_store_dwordx4 v[98:99], v[68:71], off offset:16 nt
	v_lshlrev_b32_e32 v76, 16, v86
	v_and_b32_e32 v77, 0xffff0000, v86
	v_lshlrev_b32_e32 v78, 16, v87
	v_and_b32_e32 v79, 0xffff0000, v87
	v_pk_add_f32 v[70:71], v[88:89], v[74:75]
	v_pk_add_f32 v[68:69], v[90:91], v[72:73]
	global_load_dwordx4 v[64:67], v[100:101], off
	v_pk_add_f32 v[74:75], v[92:93], v[78:79]
	v_pk_add_f32 v[72:73], v[94:95], v[76:77]
	global_store_dwordx4 v[98:99], v[68:71], off offset:512 nt
	global_store_dwordx4 v[98:99], v[72:75], off offset:528 nt
	global_load_dwordx4 v[68:71], v[100:101], off offset:256
	v_add_u32_e32 v80, 0x90, v144
	v_ashrrev_i32_e32 v81, 31, v80
	v_pk_add_f32 v[76:77], v[50:51], 0 op_sel_hi:[1,0]
	v_pk_add_f32 v[78:79], v[48:49], 0 op_sel_hi:[1,0]
	v_lshlrev_b64 v[48:49], 12, v[96:97]
	v_lshlrev_b64 v[50:51], 11, v[80:81]
	v_lshl_add_u64 v[48:49], s[76:77], 0, v[48:49]
	v_lshl_add_u64 v[50:51], s[78:79], 0, v[50:51]
	v_pk_add_f32 v[72:73], v[54:55], 0 op_sel_hi:[1,0]
	v_pk_add_f32 v[74:75], v[52:53], 0 op_sel_hi:[1,0]
	v_lshl_add_u64 v[82:83], v[48:49], 0, v[112:113]
	v_lshl_add_u64 v[84:85], v[50:51], 0, v[146:147]
	s_waitcnt vmcnt(3)
	v_lshlrev_b32_e32 v48, 16, v64
	v_and_b32_e32 v49, 0xffff0000, v64
	v_lshlrev_b32_e32 v50, 16, v65
	v_and_b32_e32 v51, 0xffff0000, v65
	v_lshlrev_b32_e32 v52, 16, v66
	v_and_b32_e32 v53, 0xffff0000, v66
	v_lshlrev_b32_e32 v54, 16, v67
	v_and_b32_e32 v55, 0xffff0000, v67
	v_pk_add_f32 v[50:51], v[62:63], v[50:51]
	v_pk_add_f32 v[48:49], v[60:61], v[48:49]
	v_pk_add_f32 v[54:55], v[58:59], v[54:55]
	v_pk_add_f32 v[52:53], v[56:57], v[52:53]
	s_waitcnt vmcnt(0)
;     __device__ __forceinline__ float rowscale(int r) const { return rsmode == 1 ? rs[r] : (rsmode == 2 ? rsqrtf((float)rs64[r] * (RSS_UNFIX * rsinv) + EPS) : 1.f); }
;     __device__ __forceinline__ void operator()(const pg8::f32x4 (&acc)[2][2][4][2], const pg8::Unit& u, int wr, int wc, int fr, int fq) const {
;     ...
;             for (int p = 0; p < 16; ++p) {
;                 const int g = p >> 1, bj = p & 1, ai = g >> 2, m = g & 3, r = row0 + ai * 128 + m * 16, c = col0 + bj * 128;
;                 if (p < 15) {
;                     const int gn = (p + 1) >> 1, rn = row0 + (gn >> 2) * 128 + (gn & 3) * 16, cn = col0 + ((p + 1) & 1) * 128;
;                     if (hasF) nb2 = *(const u32x4*)(base2 + (size_t)rn * 1024 + cn);
;                     nbb = *(const u32x4*)(baseb + (size_t)rn * 1024 + cn);
;                     if (bj == 1) nsc = rowscale(rn);
;                 }
;                 const f32x4 r0 = {bflo(cbb.x), bfhi(cbb.x), bflo(cbb.y), bfhi(cbb.y)}, r1 = {bflo(cbb.z), bfhi(cbb.z), bflo(cbb.w), bfhi(cbb.w)};
;                 const f32x4 q0 = {bflo(cb2.x), bfhi(cb2.x), bflo(cb2.y), bfhi(cb2.y)}, q1 = {bflo(cb2.z), bfhi(cb2.z), bflo(cb2.w), bfhi(cb2.w)};
;                 const f32x4 v0 = acc[ai][bj][m][0] * csc + q0 + r0, v1 = acc[ai][bj][m][1] * csc + q1 + r1;
;                 if (outF) {
;                     float* op = out + (size_t)r * 1024 + c;
;                     *(f32x4*)op = v0; *(f32x4*)(op + 4) = v1;
;                 } else {
	v_lshlrev_b32_e32 v56, 16, v68
	v_and_b32_e32 v57, 0xffff0000, v68
	v_lshlrev_b32_e32 v58, 16, v69
	v_and_b32_e32 v59, 0xffff0000, v69
	global_store_dwordx4 v[82:83], v[48:51], off nt
	global_store_dwordx4 v[82:83], v[52:55], off offset:16 nt
	v_lshlrev_b32_e32 v60, 16, v70
	v_and_b32_e32 v61, 0xffff0000, v70
	v_lshlrev_b32_e32 v62, 16, v71
	v_and_b32_e32 v63, 0xffff0000, v71
	v_pk_add_f32 v[54:55], v[72:73], v[58:59]
	v_pk_add_f32 v[52:53], v[74:75], v[56:57]
	global_load_dwordx4 v[48:51], v[84:85], off
	v_pk_add_f32 v[58:59], v[76:77], v[62:63]
	v_pk_add_f32 v[56:57], v[78:79], v[60:61]
	global_store_dwordx4 v[82:83], v[52:55], off offset:512 nt
	global_store_dwordx4 v[82:83], v[56:59], off offset:528 nt
	global_load_dwordx4 v[52:55], v[84:85], off offset:256
	v_add_u32_e32 v64, 0xa0, v144
	v_ashrrev_i32_e32 v65, 31, v64
	v_pk_add_f32 v[60:61], v[34:35], 0 op_sel_hi:[1,0]
	v_pk_add_f32 v[62:63], v[32:33], 0 op_sel_hi:[1,0]
	v_lshlrev_b64 v[32:33], 12, v[80:81]
	v_lshlrev_b64 v[34:35], 11, v[64:65]
	v_lshl_add_u64 v[32:33], s[76:77], 0, v[32:33]
	v_lshl_add_u64 v[34:35], s[78:79], 0, v[34:35]
	v_pk_add_f32 v[56:57], v[38:39], 0 op_sel_hi:[1,0]
	v_pk_add_f32 v[58:59], v[36:37], 0 op_sel_hi:[1,0]
	v_lshl_add_u64 v[66:67], v[32:33], 0, v[112:113]
	v_lshl_add_u64 v[68:69], v[34:35], 0, v[146:147]
	s_waitcnt vmcnt(3)
	v_lshlrev_b32_e32 v32, 16, v48
	v_and_b32_e32 v33, 0xffff0000, v48
	v_lshlrev_b32_e32 v34, 16, v49
	v_and_b32_e32 v35, 0xffff0000, v49
	v_lshlrev_b32_e32 v36, 16, v50
	v_and_b32_e32 v37, 0xffff0000, v50
	v_lshlrev_b32_e32 v38, 16, v51
	v_and_b32_e32 v39, 0xffff0000, v51
	v_pk_add_f32 v[34:35], v[46:47], v[34:35]
	v_pk_add_f32 v[32:33], v[44:45], v[32:33]
	v_pk_add_f32 v[38:39], v[42:43], v[38:39]
	v_pk_add_f32 v[36:37], v[40:41], v[36:37]
	s_waitcnt vmcnt(0)
	v_lshlrev_b32_e32 v40, 16, v52
	v_and_b32_e32 v41, 0xffff0000, v52
	v_lshlrev_b32_e32 v42, 16, v53
	v_and_b32_e32 v43, 0xffff0000, v53
	global_store_dwordx4 v[66:67], v[32:35], off nt
	global_store_dwordx4 v[66:67], v[36:39], off offset:16 nt
	v_lshlrev_b32_e32 v44, 16, v54
	v_and_b32_e32 v45, 0xffff0000, v54
	v_lshlrev_b32_e32 v46, 16, v55
	v_and_b32_e32 v47, 0xffff0000, v55
	v_pk_add_f32 v[38:39], v[56:57], v[42:43]
	v_pk_add_f32 v[36:37], v[58:59], v[40:41]
	global_load_dwordx4 v[32:35], v[68:69], off
	v_pk_add_f32 v[42:43], v[60:61], v[46:47]
	v_pk_add_f32 v[40:41], v[62:63], v[44:45]
	global_store_dwordx4 v[66:67], v[36:39], off offset:512 nt
	global_store_dwordx4 v[66:67], v[40:43], off offset:528 nt
	global_load_dwordx4 v[36:39], v[68:69], off offset:256
	v_add_u32_e32 v48, 0xb0, v144
	v_ashrrev_i32_e32 v49, 31, v48
	v_pk_add_f32 v[44:45], v[18:19], 0 op_sel_hi:[1,0]
	v_pk_add_f32 v[46:47], v[16:17], 0 op_sel_hi:[1,0]
	v_lshlrev_b64 v[16:17], 12, v[64:65]
	v_lshlrev_b64 v[18:19], 11, v[48:49]
	v_lshl_add_u64 v[16:17], s[76:77], 0, v[16:17]
	v_lshl_add_u64 v[18:19], s[78:79], 0, v[18:19]
	v_pk_add_f32 v[40:41], v[22:23], 0 op_sel_hi:[1,0]
	v_pk_add_f32 v[42:43], v[20:21], 0 op_sel_hi:[1,0]
	v_lshl_add_u64 v[50:51], v[16:17], 0, v[112:113]
	v_lshl_add_u64 v[52:53], v[18:19], 0, v[146:147]
	s_waitcnt vmcnt(3)
	v_lshlrev_b32_e32 v16, 16, v32
	v_and_b32_e32 v17, 0xffff0000, v32
	v_lshlrev_b32_e32 v18, 16, v33
	v_and_b32_e32 v19, 0xffff0000, v33
	v_lshlrev_b32_e32 v20, 16, v34
	v_and_b32_e32 v21, 0xffff0000, v34
	v_lshlrev_b32_e32 v22, 16, v35
	v_and_b32_e32 v23, 0xffff0000, v35
	v_pk_add_f32 v[18:19], v[30:31], v[18:19]
	v_pk_add_f32 v[16:17], v[28:29], v[16:17]
	v_pk_add_f32 v[22:23], v[26:27], v[22:23]
	v_pk_add_f32 v[20:21], v[24:25], v[20:21]
	s_waitcnt vmcnt(0)
	v_lshlrev_b32_e32 v24, 16, v36
	v_and_b32_e32 v25, 0xffff0000, v36
	v_lshlrev_b32_e32 v26, 16, v37
	v_and_b32_e32 v27, 0xffff0000, v37
	global_store_dwordx4 v[50:51], v[16:19], off nt
	global_store_dwordx4 v[50:51], v[20:23], off offset:16 nt
	v_lshlrev_b32_e32 v28, 16, v38
	v_and_b32_e32 v29, 0xffff0000, v38
	v_lshlrev_b32_e32 v30, 16, v39
	v_and_b32_e32 v31, 0xffff0000, v39
	v_pk_add_f32 v[22:23], v[40:41], v[26:27]
	v_pk_add_f32 v[20:21], v[42:43], v[24:25]
	global_load_dwordx4 v[16:19], v[52:53], off
	v_pk_add_f32 v[26:27], v[44:45], v[30:31]
	v_pk_add_f32 v[24:25], v[46:47], v[28:29]
	global_store_dwordx4 v[50:51], v[20:23], off offset:512 nt
	global_store_dwordx4 v[50:51], v[24:27], off offset:528 nt
	global_load_dwordx4 v[20:23], v[52:53], off offset:256
	v_pk_add_f32 v[30:31], v[0:1], 0 op_sel_hi:[1,0]
	v_lshlrev_b64 v[0:1], 12, v[48:49]
	v_lshl_add_u64 v[0:1], s[76:77], 0, v[0:1]
	v_pk_add_f32 v[24:25], v[6:7], 0 op_sel_hi:[1,0]
	v_pk_add_f32 v[26:27], v[4:5], 0 op_sel_hi:[1,0]
	v_pk_add_f32 v[28:29], v[2:3], 0 op_sel_hi:[1,0]
	v_lshl_add_u64 v[32:33], v[0:1], 0, v[112:113]
	s_waitcnt vmcnt(3)
	v_lshlrev_b32_e32 v0, 16, v16
	v_and_b32_e32 v1, 0xffff0000, v16
	v_lshlrev_b32_e32 v2, 16, v17
	v_and_b32_e32 v3, 0xffff0000, v17
	v_lshlrev_b32_e32 v4, 16, v18
	v_and_b32_e32 v5, 0xffff0000, v18
	v_lshlrev_b32_e32 v6, 16, v19
	v_and_b32_e32 v7, 0xffff0000, v19
	v_pk_add_f32 v[2:3], v[14:15], v[2:3]
	v_pk_add_f32 v[0:1], v[12:13], v[0:1]
	v_pk_add_f32 v[6:7], v[10:11], v[6:7]
	v_pk_add_f32 v[4:5], v[8:9], v[4:5]
	s_waitcnt vmcnt(0)
	v_lshlrev_b32_e32 v8, 16, v20
	v_and_b32_e32 v9, 0xffff0000, v20
	v_lshlrev_b32_e32 v10, 16, v21
	v_and_b32_e32 v11, 0xffff0000, v21
	v_lshlrev_b32_e32 v12, 16, v22
	v_and_b32_e32 v13, 0xffff0000, v22
	v_lshlrev_b32_e32 v14, 16, v23
	v_and_b32_e32 v15, 0xffff0000, v23
	global_store_dwordx4 v[32:33], v[0:3], off nt
	global_store_dwordx4 v[32:33], v[4:7], off offset:16 nt
	s_nop 0
	v_pk_add_f32 v[2:3], v[24:25], v[10:11]
	v_pk_add_f32 v[0:1], v[26:27], v[8:9]
	v_pk_add_f32 v[6:7], v[28:29], v[14:15]
	v_pk_add_f32 v[4:5], v[30:31], v[12:13]
	global_store_dwordx4 v[32:33], v[0:3], off offset:512 nt
	global_store_dwordx4 v[32:33], v[4:7], off offset:528 nt
	s_cbranch_vccnz .LBB0_1031
	s_andn2_b64 vcc, exec, s[2:3]
	s_cbranch_vccnz .LBB0_1030
	s_barrier
	s_branch .LBB0_1030
